# attention: V fragment address and first V read issued inside the MFMA result wait window (shorter s_nop), on top of head-split QK block
# baseline (speedup 1.0000x reference)
.LBB0_885:
	v_lshl_add_u32 v254, s68, 6, v202
	ds_read_b128 v[246:249], v254 offset:17920
	s_nop 6
	s_cmp_lg_u64 s[64:65], 0
	s_cbranch_scc1 .Lhwat0_full
	v_max_f32_e32 v203, v80, v81
	v_max_f32_e32 v205, v64, v65
	v_max3_f32 v203, v203, v82, v83
	v_max3_f32 v205, v205, v66, v67
	v_max3_f32 v203, v203, v84, v85
	v_max3_f32 v205, v205, v68, v69
	v_max3_f32 v203, v203, v86, v87
	v_max3_f32 v205, v205, v70, v71
	v_max3_f32 v203, v203, v88, v89
	v_max3_f32 v205, v205, v72, v73
	v_max3_f32 v203, v203, v90, v91
	v_max3_f32 v205, v205, v74, v75
	v_max3_f32 v203, v203, v92, v93
	v_max3_f32 v205, v205, v76, v77
	v_max3_f32 v203, v203, v94, v95
	v_max3_f32 v205, v205, v78, v79
	v_max_f32_e32 v204, v203, v205
	v_cmp_lt_f32_e32 vcc, s83, v204
	s_cbranch_vccnz .Lhwat0_full
.LBB0_887:
	v_exp_f32_e32 v209, v80
	v_exp_f32_e32 v211, v81
	v_exp_f32_e32 v213, v82
	v_exp_f32_e32 v215, v83
	ds_read_b128 v[80:83], v254 offset:13312
	v_exp_f32_e32 v217, v84
	v_exp_f32_e32 v219, v85
	v_exp_f32_e32 v221, v86
	v_exp_f32_e32 v223, v87
	v_exp_f32_e32 v208, v64
	v_exp_f32_e32 v210, v65
	v_exp_f32_e32 v212, v66
	v_exp_f32_e32 v214, v67
	v_exp_f32_e32 v216, v68
	v_exp_f32_e32 v218, v69
	v_exp_f32_e32 v220, v70
	v_exp_f32_e32 v222, v71
	v_cvt_pk_bf16_f32 v64, v209, v211
	v_cvt_pk_bf16_f32 v65, v213, v215
	v_cvt_pk_bf16_f32 v66, v217, v219
	v_cvt_pk_bf16_f32 v67, v221, v223
	v_cvt_pk_bf16_f32 v68, v208, v210
	v_cvt_pk_bf16_f32 v69, v212, v214
	v_cvt_pk_bf16_f32 v70, v216, v218
	v_cvt_pk_bf16_f32 v71, v220, v222
	ds_read_b128 v[84:87], v254 offset:13344
	s_waitcnt lgkmcnt(1)
	v_mfma_f32_32x32x16_bf16 v[48:63], v[80:83], v[64:67], v[48:63]
	v_exp_f32_e32 v225, v88
	v_exp_f32_e32 v224, v72
	v_exp_f32_e32 v88, v73
	v_exp_f32_e32 v89, v89
	v_exp_f32_e32 v227, v90
	v_exp_f32_e32 v91, v91
	v_exp_f32_e32 v229, v92
	v_mfma_f32_32x32x16_bf16 v[16:31], v[80:83], v[68:71], v[16:31]
	ds_read_b128 v[80:83], v254 offset:17952
	v_exp_f32_e32 v93, v93
	v_exp_f32_e32 v231, v94
	v_exp_f32_e32 v95, v95
	v_exp_f32_e32 v226, v74
	v_exp_f32_e32 v90, v75
	v_exp_f32_e32 v228, v76
	s_waitcnt lgkmcnt(2)
	v_mfma_f32_32x32x16_bf16 v[32:47], v[246:249], v[64:67], v[32:47]
	v_exp_f32_e32 v92, v77
	v_add_f32_e32 v64, v210, v208
	v_add_f32_e32 v65, v211, v209
	v_exp_f32_e32 v230, v78
	v_add_f32_e32 v208, v212, v64
	v_add_f32_e32 v209, v213, v65
	v_exp_f32_e32 v94, v79
	v_add_f32_e32 v72, v214, v208
	v_add_f32_e32 v73, v215, v209
	v_mfma_f32_32x32x16_bf16 v[0:15], v[246:249], v[68:71], v[0:15]
	v_add_f32_e64 v72, v216, v72
	v_add_f32_e64 v73, v217, v73
	v_cvt_pk_bf16_f32 v64, v225, v89
	v_add_f32_e64 v72, v218, v72
	v_add_f32_e64 v73, v219, v73
	v_cvt_pk_bf16_f32 v65, v227, v91
	v_add_f32_e32 v72, v220, v72
	v_add_f32_e32 v73, v221, v73
	v_cvt_pk_bf16_f32 v66, v229, v93
	v_add_f32_e32 v72, v222, v72
	v_add_f32_e32 v73, v223, v73
	v_cvt_pk_bf16_f32 v67, v231, v95
	v_cvt_pk_bf16_f32 v68, v224, v88
	v_cvt_pk_bf16_f32 v69, v226, v90
	v_cvt_pk_bf16_f32 v70, v228, v92
	v_cvt_pk_bf16_f32 v71, v230, v94
	v_add_f32_e32 v72, v224, v72
	v_add_f32_e32 v73, v225, v73
	s_waitcnt lgkmcnt(1)
	v_mfma_f32_32x32x16_bf16 v[48:63], v[84:87], v[64:67], v[48:63]
	v_add_f32_e64 v72, v88, v72
	v_add_f32_e64 v73, v89, v73
	s_xor_b64 s[28:29], s[66:67], -1
	s_mov_b32 s68, 1
	s_mov_b64 s[66:67], 0
	s_and_b64 vcc, exec, s[28:29]
	v_mfma_f32_32x32x16_bf16 v[16:31], v[84:87], v[68:71], v[16:31]
	s_waitcnt lgkmcnt(0)
	v_mfma_f32_32x32x16_bf16 v[32:47], v[80:83], v[64:67], v[32:47]
	v_add_f32_e64 v64, v226, v72
	v_add_f32_e64 v65, v227, v73
	v_add_f32_e64 v64, v90, v64
	v_add_f32_e64 v65, v91, v65
	v_add_f32_e64 v64, v228, v64
	v_add_f32_e64 v65, v229, v65
	v_add_f32_e32 v64, v92, v64
	v_add_f32_e32 v65, v93, v65
	v_mfma_f32_32x32x16_bf16 v[0:15], v[80:83], v[68:71], v[0:15]
	v_add_f32_e64 v64, v230, v64
	v_add_f32_e64 v65, v231, v65
	v_add_f32_e64 v64, v94, v64
	v_add_f32_e64 v65, v95, v65
	v_add_f32_e64 v150, v150, v64
	v_add_f32_e64 v151, v151, v65
	s_cbranch_vccnz .LBB0_889
	s_mov_b64 s[64:65], 0
	s_and_b64 vcc, exec, s[62:63]
	v_lshl_or_b32 v203, s68, 5, v190
	s_mov_b64 s[28:29], -1
	s_cbranch_vccz .LBB0_882
	s_branch .LBB0_883

.LBB0_2119:
	v_lshl_add_u32 v254, s68, 6, v202
	ds_read_b128 v[246:249], v254 offset:17920
	s_nop 6
	s_cmp_lg_u64 s[64:65], 0
	s_cbranch_scc1 .Lhwat1_full
	v_max_f32_e32 v203, v80, v81
	v_max_f32_e32 v205, v64, v65
	v_max3_f32 v203, v203, v82, v83
	v_max3_f32 v205, v205, v66, v67
	v_max3_f32 v203, v203, v84, v85
	v_max3_f32 v205, v205, v68, v69
	v_max3_f32 v203, v203, v86, v87
	v_max3_f32 v205, v205, v70, v71
	v_max3_f32 v203, v203, v88, v89
	v_max3_f32 v205, v205, v72, v73
	v_max3_f32 v203, v203, v90, v91
	v_max3_f32 v205, v205, v74, v75
	v_max3_f32 v203, v203, v92, v93
	v_max3_f32 v205, v205, v76, v77
	v_max3_f32 v203, v203, v94, v95
	v_max3_f32 v205, v205, v78, v79
	v_max_f32_e32 v204, v203, v205
	v_cmp_lt_f32_e32 vcc, s82, v204
	s_cbranch_vccnz .Lhwat1_full
.LBB0_2121:
	v_exp_f32_e32 v209, v80
	v_exp_f32_e32 v211, v81
	v_exp_f32_e32 v213, v82
	v_exp_f32_e32 v215, v83
	ds_read_b128 v[80:83], v254 offset:13312
	v_exp_f32_e32 v217, v84
	v_exp_f32_e32 v219, v85
	v_exp_f32_e32 v221, v86
	v_exp_f32_e32 v223, v87
	v_exp_f32_e32 v208, v64
	v_exp_f32_e32 v210, v65
	v_exp_f32_e32 v212, v66
	v_exp_f32_e32 v214, v67
	v_exp_f32_e32 v216, v68
	v_exp_f32_e32 v218, v69
	v_exp_f32_e32 v220, v70
	v_exp_f32_e32 v222, v71
	v_cvt_pk_bf16_f32 v64, v209, v211
	v_cvt_pk_bf16_f32 v65, v213, v215
	v_cvt_pk_bf16_f32 v66, v217, v219
	v_cvt_pk_bf16_f32 v67, v221, v223
	v_cvt_pk_bf16_f32 v68, v208, v210
	v_cvt_pk_bf16_f32 v69, v212, v214
	v_cvt_pk_bf16_f32 v70, v216, v218
	v_cvt_pk_bf16_f32 v71, v220, v222
	ds_read_b128 v[84:87], v254 offset:13344
	s_waitcnt lgkmcnt(1)
	v_mfma_f32_32x32x16_bf16 v[48:63], v[80:83], v[64:67], v[48:63]
	v_exp_f32_e32 v225, v88
	v_exp_f32_e32 v224, v72
	v_exp_f32_e32 v88, v73
	v_exp_f32_e32 v89, v89
	v_exp_f32_e32 v227, v90
	v_exp_f32_e32 v91, v91
	v_exp_f32_e32 v229, v92
	v_mfma_f32_32x32x16_bf16 v[16:31], v[80:83], v[68:71], v[16:31]
	ds_read_b128 v[80:83], v254 offset:17952
	v_exp_f32_e32 v93, v93
	v_exp_f32_e32 v231, v94
	v_exp_f32_e32 v95, v95
	v_exp_f32_e32 v226, v74
	v_exp_f32_e32 v90, v75
	v_exp_f32_e32 v228, v76
	s_waitcnt lgkmcnt(2)
	v_mfma_f32_32x32x16_bf16 v[32:47], v[246:249], v[64:67], v[32:47]
	v_exp_f32_e32 v92, v77
	v_add_f32_e32 v64, v210, v208
	v_add_f32_e32 v65, v211, v209
	v_exp_f32_e32 v230, v78
	v_add_f32_e32 v208, v212, v64
	v_add_f32_e32 v209, v213, v65
	v_exp_f32_e32 v94, v79
	v_add_f32_e32 v72, v214, v208
	v_add_f32_e32 v73, v215, v209
	v_mfma_f32_32x32x16_bf16 v[0:15], v[246:249], v[68:71], v[0:15]
	v_add_f32_e64 v72, v216, v72
	v_add_f32_e64 v73, v217, v73
	v_cvt_pk_bf16_f32 v64, v225, v89
	v_add_f32_e64 v72, v218, v72
	v_add_f32_e64 v73, v219, v73
	v_cvt_pk_bf16_f32 v65, v227, v91
	v_add_f32_e32 v72, v220, v72
	v_add_f32_e32 v73, v221, v73
	v_cvt_pk_bf16_f32 v66, v229, v93
	v_add_f32_e32 v72, v222, v72
	v_add_f32_e32 v73, v223, v73
	v_cvt_pk_bf16_f32 v67, v231, v95
	v_cvt_pk_bf16_f32 v68, v224, v88
	v_cvt_pk_bf16_f32 v69, v226, v90
	v_cvt_pk_bf16_f32 v70, v228, v92
	v_cvt_pk_bf16_f32 v71, v230, v94
	v_add_f32_e32 v72, v224, v72
	v_add_f32_e32 v73, v225, v73
	s_waitcnt lgkmcnt(1)
	v_mfma_f32_32x32x16_bf16 v[48:63], v[84:87], v[64:67], v[48:63]
	v_add_f32_e64 v72, v88, v72
	v_add_f32_e64 v73, v89, v73
	s_xor_b64 s[34:35], s[66:67], -1
	s_mov_b32 s68, 1
	s_mov_b64 s[66:67], 0
	s_and_b64 vcc, exec, s[34:35]
	v_mfma_f32_32x32x16_bf16 v[16:31], v[84:87], v[68:71], v[16:31]
	s_waitcnt lgkmcnt(0)
	v_mfma_f32_32x32x16_bf16 v[32:47], v[80:83], v[64:67], v[32:47]
	v_add_f32_e64 v64, v226, v72
	v_add_f32_e64 v65, v227, v73
	v_add_f32_e64 v64, v90, v64
	v_add_f32_e64 v65, v91, v65
	v_add_f32_e64 v64, v228, v64
	v_add_f32_e64 v65, v229, v65
	v_add_f32_e32 v64, v92, v64
	v_add_f32_e32 v65, v93, v65
	v_mfma_f32_32x32x16_bf16 v[0:15], v[80:83], v[68:71], v[0:15]
	v_add_f32_e64 v64, v230, v64
	v_add_f32_e64 v65, v231, v65
	v_add_f32_e64 v64, v94, v64
	v_add_f32_e64 v65, v95, v65
	v_add_f32_e64 v150, v150, v64
	v_add_f32_e64 v151, v151, v65
	s_cbranch_vccnz .LBB0_2123
	s_mov_b64 s[64:65], 0
	s_and_b64 vcc, exec, s[62:63]
	v_lshl_or_b32 v203, s68, 5, v190
	s_mov_b64 s[34:35], -1
	s_cbranch_vccz .LBB0_2116
	s_branch .LBB0_2117

	.amdhsa_kernel _Z14fwd_megakernel6Params
		.amdhsa_group_segment_fixed_size 65536
		.amdhsa_private_segment_fixed_size 0
		.amdhsa_kernarg_size 504
		.amdhsa_user_sgpr_count 2
		.amdhsa_user_sgpr_dispatch_ptr 0
		.amdhsa_user_sgpr_queue_ptr 0
		.amdhsa_user_sgpr_kernarg_segment_ptr 1
		.amdhsa_user_sgpr_dispatch_id 0
		.amdhsa_user_sgpr_kernarg_preload_length 0
		.amdhsa_user_sgpr_kernarg_preload_offset 0
		.amdhsa_user_sgpr_private_segment_size 0
		.amdhsa_uses_dynamic_stack 0
		.amdhsa_enable_private_segment 0
		.amdhsa_system_sgpr_workgroup_id_x 1
		.amdhsa_system_sgpr_workgroup_id_y 0
		.amdhsa_system_sgpr_workgroup_id_z 0
		.amdhsa_system_sgpr_workgroup_info 0
		.amdhsa_system_vgpr_workitem_id 2
		.amdhsa_next_free_vgpr 255
		.amdhsa_next_free_sgpr 102
		.amdhsa_accum_offset 256
		.amdhsa_reserve_vcc 1
		.amdhsa_float_round_mode_32 0
		.amdhsa_float_round_mode_16_64 0
		.amdhsa_float_denorm_mode_32 3
		.amdhsa_float_denorm_mode_16_64 3
		.amdhsa_dx10_clamp 1
		.amdhsa_ieee_mode 1
		.amdhsa_fp16_overflow 0
		.amdhsa_tg_split 0
		.amdhsa_exception_fp_ieee_invalid_op 0
		.amdhsa_exception_fp_denorm_src 0
		.amdhsa_exception_fp_ieee_div_zero 0
		.amdhsa_exception_fp_ieee_overflow 0
		.amdhsa_exception_fp_ieee_underflow 0
		.amdhsa_exception_fp_ieee_inexact 0
		.amdhsa_exception_int_div_zero 0
	.end_amdhsa_kernel

amdhsa.kernels:
  - .agpr_count:     0
    .args:
      - .offset:         0
        .size:           248
        .value_kind:     by_value
      - .offset:         248
        .size:           4
        .value_kind:     hidden_block_count_x
      - .offset:         252
        .size:           4
        .value_kind:     hidden_block_count_y
      - .offset:         256
        .size:           4
        .value_kind:     hidden_block_count_z
      - .offset:         260
        .size:           2
        .value_kind:     hidden_group_size_x
      - .offset:         262
        .size:           2
        .value_kind:     hidden_group_size_y
      - .offset:         264
        .size:           2
        .value_kind:     hidden_group_size_z
      - .offset:         266
        .size:           2
        .value_kind:     hidden_remainder_x
      - .offset:         268
        .size:           2
        .value_kind:     hidden_remainder_y
      - .offset:         270
        .size:           2
        .value_kind:     hidden_remainder_z
      - .offset:         288
        .size:           8
        .value_kind:     hidden_global_offset_x
      - .offset:         296
        .size:           8
        .value_kind:     hidden_global_offset_y
      - .offset:         304
        .size:           8
        .value_kind:     hidden_global_offset_z
      - .offset:         312
        .size:           2
        .value_kind:     hidden_grid_dims
      - .offset:         336
        .size:           8
        .value_kind:     hidden_multigrid_sync_arg
    .group_segment_fixed_size: 65536
    .kernarg_segment_align: 8
    .kernarg_segment_size: 504
    .language:       OpenCL C
    .language_version:
      - 2
      - 0
    .max_flat_workgroup_size: 256
    .name:           _Z14fwd_megakernel6Params
    .private_segment_fixed_size: 0
    .sgpr_count:     104
    .sgpr_spill_count: 4
    .symbol:         _Z14fwd_megakernel6Params.kd
    .uniform_work_group_size: 1
    .uses_dynamic_stack: false
    .vgpr_count:     255
    .vgpr_spill_count: 0
    .wavefront_size: 64
